# v22 + SwiGLU epilogue: 64 v_pk_mul_f32 split into scalar v_mul_f32 pairs (bit-identical)
# baseline (speedup 1.0000x reference)
; __device__ __forceinline__ unsigned cvt_pk_bf16(float lo, float hi) { f32x2cv v = {lo, hi}; bf16x2cv b = __builtin_convertvector(v, bf16x2cv); return __builtin_bit_cast(unsigned, b); }
;     __device__ __forceinline__ void operator()(const f32x4 (&acc)[2][2][4][2], const Unit& u, int wr, int wc, int fr, int fq) const {
;         const int row0 = u.pm * BM + wr * 64 + fr; const int col0 = u.pn * HALF + wc * 32 + 8 * fq;
; #pragma unroll
;         for (int ai = 0; ai < 2; ++ai)
; #pragma unroll
;             for (int m = 0; m < 4; ++m) { bf16_t* rowp = O + (size_t)(row0 + ai * HALF + m * 16) * ldc + col0;
;                 float hv[8];
; #pragma unroll
;                 for (int n = 0; n < 2; ++n)
; #pragma unroll
;                     for (int e = 0; e < 4; ++e) { const float ag = acc[ai][0][m][n][e], au = acc[ai][1][m][n][e];
;                         hv[n * 4 + e] = ag * au * __builtin_amdgcn_rcpf(1.0f + __builtin_amdgcn_exp2f(ag)); }
;                 u32x4 w; w.x = cvt_pk_bf16(hv[0], hv[1]); w.y = cvt_pk_bf16(hv[2], hv[3]); w.z = cvt_pk_bf16(hv[4], hv[5]); w.w = cvt_pk_bf16(hv[6], hv[7]);
;                 __builtin_nontemporal_store(w, (u32x4*)rowp); }
.LBB0_371:
	v_lshl_add_u32 v140, s49, 8, v142
	v_ashrrev_i32_e32 v141, 31, v140
	v_lshlrev_b64 v[148:149], 13, v[140:141]
	v_exp_f32_e32 v141, v122
	v_mul_f32_e32 v128, v124, v128
	v_mul_f32_e32 v129, v125, v129
	v_exp_f32_e32 v124, v124
	v_exp_f32_e32 v125, v125
	v_add_f32_e32 v141, 1.0, v141
	v_rcp_f32_e32 v154, v141
	v_exp_f32_e32 v141, v123
	v_mul_f32_e32 v122, v122, v126
	v_mul_f32_e32 v123, v123, v127
	v_exp_f32_e32 v126, v114
	v_exp_f32_e32 v127, v115
	v_mul_f32_e32 v114, v114, v118
	v_mul_f32_e32 v115, v115, v119
	v_add_f32_e32 v141, 1.0, v141
	v_add_f32_e32 v126, 1.0, v126
	v_add_f32_e32 v127, 1.0, v127
	v_rcp_f32_e32 v126, v126
	v_rcp_f32_e32 v127, v127
	v_add_f32_e32 v124, 1.0, v124
	v_add_f32_e32 v125, 1.0, v125
	v_rcp_f32_e32 v155, v141
	v_mul_f32_e32 v126, v126, v114
	v_mul_f32_e32 v127, v127, v115
	v_exp_f32_e32 v114, v116
	v_exp_f32_e32 v115, v117
	v_rcp_f32_e32 v124, v124
	v_rcp_f32_e32 v125, v125
	v_add_f32_e32 v114, 1.0, v114
	v_add_f32_e32 v115, 1.0, v115
	v_rcp_f32_e32 v114, v114
	v_rcp_f32_e32 v115, v115
	v_lshl_or_b32 v146, s33, 7, v144
	v_ashrrev_i32_e32 v147, 31, v146
	v_mul_f32_e32 v120, v116, v120
	v_mul_f32_e32 v121, v117, v121
	v_lshl_add_u64 v[148:149], s[92:93], 0, v[148:149]
	v_mul_f32_e32 v122, v154, v122
	v_mul_f32_e32 v123, v155, v123
	v_mul_f32_e32 v124, v124, v128
	v_mul_f32_e32 v125, v125, v129
	v_mul_f32_e32 v128, v114, v120
	v_mul_f32_e32 v129, v115, v121
	v_lshlrev_b64 v[116:117], 1, v[146:147]
	v_lshl_add_u64 v[114:115], v[148:149], 0, v[116:117]
	v_cvt_pk_bf16_f32 v118, v122, v123
	v_cvt_pk_bf16_f32 v119, v124, v125
	v_cvt_pk_bf16_f32 v120, v126, v127
	v_cvt_pk_bf16_f32 v121, v128, v129
	global_store_dwordx4 v[114:115], v[118:121], off nt
	v_mul_f32_e32 v112, v108, v112
	v_mul_f32_e32 v113, v109, v113
	v_exp_f32_e32 v108, v108
	v_exp_f32_e32 v120, v106
	v_exp_f32_e32 v121, v107
	v_mul_f32_e32 v106, v106, v110
	v_mul_f32_e32 v107, v107, v111
	v_exp_f32_e32 v110, v98
	v_exp_f32_e32 v111, v99
	v_mul_f32_e32 v98, v98, v102
	v_mul_f32_e32 v99, v99, v103
	v_exp_f32_e32 v109, v109
	v_add_f32_e32 v110, 1.0, v110
	v_add_f32_e32 v111, 1.0, v111
	v_rcp_f32_e32 v110, v110
	v_rcp_f32_e32 v111, v111
	v_add_f32_e32 v120, 1.0, v120
	v_add_f32_e32 v121, 1.0, v121
	v_add_f32_e32 v108, 1.0, v108
	v_mul_f32_e32 v102, v110, v98
	v_mul_f32_e32 v103, v111, v99
	v_exp_f32_e32 v98, v100
	v_exp_f32_e32 v99, v101
	v_add_f32_e32 v109, 1.0, v109
	v_rcp_f32_e32 v120, v120
	v_add_f32_e32 v98, 1.0, v98
	v_add_f32_e32 v99, 1.0, v99
	v_rcp_f32_e32 v121, v121
	v_rcp_f32_e32 v108, v108
	v_rcp_f32_e32 v109, v109
	v_rcp_f32_e32 v98, v98
	v_rcp_f32_e32 v99, v99
	v_or_b32_e32 v118, 16, v140
	v_ashrrev_i32_e32 v119, 31, v118
	v_lshlrev_b64 v[118:119], 13, v[118:119]
	v_mul_f32_e32 v104, v100, v104
	v_mul_f32_e32 v105, v101, v105
	v_lshl_add_u64 v[118:119], s[92:93], 0, v[118:119]
	v_mul_f32_e32 v106, v120, v106
	v_mul_f32_e32 v107, v121, v107
	v_mul_f32_e32 v108, v108, v112
	v_mul_f32_e32 v109, v109, v113
	v_mul_f32_e32 v104, v98, v104
	v_mul_f32_e32 v105, v99, v105
	v_lshl_add_u64 v[110:111], v[118:119], 0, v[116:117]
	v_cvt_pk_bf16_f32 v98, v106, v107
	v_cvt_pk_bf16_f32 v99, v108, v109
	v_cvt_pk_bf16_f32 v100, v102, v103
	v_cvt_pk_bf16_f32 v101, v104, v105
	global_store_dwordx4 v[110:111], v[98:101], off nt
	v_mul_f32_e32 v96, v92, v96
	v_mul_f32_e32 v97, v93, v97
	v_exp_f32_e32 v92, v92
	v_exp_f32_e32 v100, v90
	v_exp_f32_e32 v101, v91
	v_mul_f32_e32 v90, v90, v94
	v_mul_f32_e32 v91, v91, v95
	v_exp_f32_e32 v94, v82
	v_exp_f32_e32 v95, v83
	v_mul_f32_e32 v82, v82, v86
	v_mul_f32_e32 v83, v83, v87
	v_exp_f32_e32 v93, v93
	v_add_f32_e32 v94, 1.0, v94
	v_add_f32_e32 v95, 1.0, v95
	v_rcp_f32_e32 v94, v94
	v_rcp_f32_e32 v95, v95
	v_add_f32_e32 v100, 1.0, v100
	v_add_f32_e32 v101, 1.0, v101
	v_add_f32_e32 v92, 1.0, v92
	v_mul_f32_e32 v86, v94, v82
	v_mul_f32_e32 v87, v95, v83
	v_exp_f32_e32 v82, v84
	v_exp_f32_e32 v83, v85
	v_add_f32_e32 v93, 1.0, v93
	v_rcp_f32_e32 v100, v100
	v_add_f32_e32 v82, 1.0, v82
	v_add_f32_e32 v83, 1.0, v83
	v_rcp_f32_e32 v101, v101
	v_rcp_f32_e32 v92, v92
	v_rcp_f32_e32 v93, v93
	v_rcp_f32_e32 v82, v82
	v_rcp_f32_e32 v83, v83
	v_or_b32_e32 v98, 32, v140
	v_ashrrev_i32_e32 v99, 31, v98
	v_lshlrev_b64 v[98:99], 13, v[98:99]
	v_mul_f32_e32 v88, v84, v88
	v_mul_f32_e32 v89, v85, v89
	v_lshl_add_u64 v[98:99], s[92:93], 0, v[98:99]
	v_mul_f32_e32 v90, v100, v90
	v_mul_f32_e32 v91, v101, v91
	v_mul_f32_e32 v92, v92, v96
	v_mul_f32_e32 v93, v93, v97
	v_mul_f32_e32 v88, v82, v88
	v_mul_f32_e32 v89, v83, v89
	v_lshl_add_u64 v[94:95], v[98:99], 0, v[116:117]
	v_cvt_pk_bf16_f32 v82, v90, v91
	v_cvt_pk_bf16_f32 v83, v92, v93
	v_cvt_pk_bf16_f32 v84, v86, v87
	v_cvt_pk_bf16_f32 v85, v88, v89
	global_store_dwordx4 v[94:95], v[82:85], off nt
	v_mul_f32_e32 v80, v76, v80
	v_mul_f32_e32 v81, v77, v81
	v_exp_f32_e32 v76, v76
	v_exp_f32_e32 v84, v74
	v_exp_f32_e32 v85, v75
	v_mul_f32_e32 v74, v74, v78
	v_mul_f32_e32 v75, v75, v79
	v_exp_f32_e32 v78, v66
	v_exp_f32_e32 v79, v67
	v_mul_f32_e32 v66, v66, v70
	v_mul_f32_e32 v67, v67, v71
	v_exp_f32_e32 v77, v77
	v_add_f32_e32 v78, 1.0, v78
	v_add_f32_e32 v79, 1.0, v79
	v_rcp_f32_e32 v78, v78
	v_rcp_f32_e32 v79, v79
	v_add_f32_e32 v84, 1.0, v84
	v_add_f32_e32 v85, 1.0, v85
	v_add_f32_e32 v76, 1.0, v76
	v_mul_f32_e32 v70, v78, v66
	v_mul_f32_e32 v71, v79, v67
	v_exp_f32_e32 v66, v68
	v_exp_f32_e32 v67, v69
	v_add_f32_e32 v77, 1.0, v77
	v_rcp_f32_e32 v84, v84
	v_add_f32_e32 v66, 1.0, v66
	v_add_f32_e32 v67, 1.0, v67
	v_rcp_f32_e32 v85, v85
	v_rcp_f32_e32 v76, v76
	v_rcp_f32_e32 v77, v77
	v_rcp_f32_e32 v66, v66
	v_rcp_f32_e32 v67, v67
	v_or_b32_e32 v82, 48, v140
	v_ashrrev_i32_e32 v83, 31, v82
; __device__ __forceinline__ unsigned cvt_pk_bf16(float lo, float hi) { f32x2cv v = {lo, hi}; bf16x2cv b = __builtin_convertvector(v, bf16x2cv); return __builtin_bit_cast(unsigned, b); }
;     __device__ __forceinline__ void operator()(const f32x4 (&acc)[2][2][4][2], const Unit& u, int wr, int wc, int fr, int fq) const {
;     ...
;             for (int m = 0; m < 4; ++m) { bf16_t* rowp = O + (size_t)(row0 + ai * HALF + m * 16) * ldc + col0;
;                 float hv[8];
; #pragma unroll
;                 for (int n = 0; n < 2; ++n)
; #pragma unroll
;                     for (int e = 0; e < 4; ++e) { const float ag = acc[ai][0][m][n][e], au = acc[ai][1][m][n][e];
;                         hv[n * 4 + e] = ag * au * __builtin_amdgcn_rcpf(1.0f + __builtin_amdgcn_exp2f(ag)); }
;                 u32x4 w; w.x = cvt_pk_bf16(hv[0], hv[1]); w.y = cvt_pk_bf16(hv[2], hv[3]); w.z = cvt_pk_bf16(hv[4], hv[5]); w.w = cvt_pk_bf16(hv[6], hv[7]);
;                 __builtin_nontemporal_store(w, (u32x4*)rowp); }
	v_lshlrev_b64 v[82:83], 13, v[82:83]
	v_mul_f32_e32 v72, v68, v72
	v_mul_f32_e32 v73, v69, v73
	v_lshl_add_u64 v[82:83], s[92:93], 0, v[82:83]
	v_mul_f32_e32 v74, v84, v74
	v_mul_f32_e32 v75, v85, v75
	v_mul_f32_e32 v76, v76, v80
	v_mul_f32_e32 v77, v77, v81
	v_mul_f32_e32 v72, v66, v72
	v_mul_f32_e32 v73, v67, v73
	v_lshl_add_u64 v[78:79], v[82:83], 0, v[116:117]
	v_cvt_pk_bf16_f32 v66, v74, v75
	v_cvt_pk_bf16_f32 v67, v76, v77
	v_cvt_pk_bf16_f32 v68, v70, v71
	v_cvt_pk_bf16_f32 v69, v72, v73
	global_store_dwordx4 v[78:79], v[66:69], off nt
	v_mul_f32_e32 v64, v60, v64
	v_mul_f32_e32 v65, v61, v65
	v_exp_f32_e32 v60, v60
	v_exp_f32_e32 v66, v58
	v_exp_f32_e32 v67, v59
	v_mul_f32_e32 v58, v58, v62
	v_mul_f32_e32 v59, v59, v63
	v_exp_f32_e32 v62, v50
	v_exp_f32_e32 v63, v51
	v_mul_f32_e32 v50, v50, v54
	v_mul_f32_e32 v51, v51, v55
	v_exp_f32_e32 v61, v61
	v_add_f32_e32 v62, 1.0, v62
	v_add_f32_e32 v63, 1.0, v63
	v_rcp_f32_e32 v62, v62
	v_rcp_f32_e32 v63, v63
	v_add_f32_e32 v66, 1.0, v66
	v_add_f32_e32 v67, 1.0, v67
	v_add_f32_e32 v60, 1.0, v60
	v_mul_f32_e32 v54, v62, v50
	v_mul_f32_e32 v55, v63, v51
	v_exp_f32_e32 v50, v52
	v_exp_f32_e32 v51, v53
	v_add_f32_e32 v61, 1.0, v61
	v_rcp_f32_e32 v66, v66
	v_add_f32_e32 v50, 1.0, v50
	v_add_f32_e32 v51, 1.0, v51
	v_rcp_f32_e32 v67, v67
	v_rcp_f32_e32 v60, v60
	v_rcp_f32_e32 v61, v61
	v_rcp_f32_e32 v50, v50
	v_rcp_f32_e32 v51, v51
	v_mul_f32_e32 v56, v52, v56
	v_mul_f32_e32 v57, v53, v57
	s_mov_b32 s9, 0x100000
	v_mul_f32_e32 v58, v66, v58
	v_mul_f32_e32 v59, v67, v59
	v_mul_f32_e32 v60, v60, v64
	v_mul_f32_e32 v61, v61, v65
	v_mul_f32_e32 v56, v50, v56
	v_mul_f32_e32 v57, v51, v57
	v_cvt_pk_bf16_f32 v52, v54, v55
	v_add_co_u32_e32 v54, vcc, s9, v114
	v_cvt_pk_bf16_f32 v50, v58, v59
	v_cvt_pk_bf16_f32 v51, v60, v61
	v_cvt_pk_bf16_f32 v53, v56, v57
	v_addc_co_u32_e32 v55, vcc, 0, v115, vcc
	global_store_dwordx4 v[54:55], v[50:53], off nt
	v_mul_f32_e32 v48, v44, v48
	v_mul_f32_e32 v49, v45, v49
	v_exp_f32_e32 v44, v44
	v_exp_f32_e32 v50, v42
	v_exp_f32_e32 v51, v43
	v_mul_f32_e32 v42, v42, v46
	v_mul_f32_e32 v43, v43, v47
	v_exp_f32_e32 v46, v34
	v_exp_f32_e32 v47, v35
	v_mul_f32_e32 v34, v34, v38
	v_mul_f32_e32 v35, v35, v39
	v_exp_f32_e32 v45, v45
	v_add_f32_e32 v46, 1.0, v46
	v_add_f32_e32 v47, 1.0, v47
	v_rcp_f32_e32 v46, v46
	v_rcp_f32_e32 v47, v47
	v_add_f32_e32 v50, 1.0, v50
	v_add_f32_e32 v51, 1.0, v51
	v_add_f32_e32 v44, 1.0, v44
	v_mul_f32_e32 v38, v46, v34
	v_mul_f32_e32 v39, v47, v35
	v_exp_f32_e32 v34, v36
	v_exp_f32_e32 v35, v37
	v_add_f32_e32 v45, 1.0, v45
	v_rcp_f32_e32 v50, v50
	v_add_f32_e32 v34, 1.0, v34
	v_add_f32_e32 v35, 1.0, v35
	v_rcp_f32_e32 v51, v51
	v_rcp_f32_e32 v44, v44
	v_rcp_f32_e32 v45, v45
	v_rcp_f32_e32 v34, v34
	v_rcp_f32_e32 v35, v35
	v_mul_f32_e32 v40, v36, v40
	v_mul_f32_e32 v41, v37, v41
	s_mov_b32 s9, 0x120000
	v_mul_f32_e32 v42, v50, v42
	v_mul_f32_e32 v43, v51, v43
	v_mul_f32_e32 v44, v44, v48
	v_mul_f32_e32 v45, v45, v49
	v_mul_f32_e32 v40, v34, v40
	v_mul_f32_e32 v41, v35, v41
	v_cvt_pk_bf16_f32 v36, v38, v39
	v_add_co_u32_e32 v38, vcc, s9, v114
	v_cvt_pk_bf16_f32 v34, v42, v43
	v_cvt_pk_bf16_f32 v35, v44, v45
	v_cvt_pk_bf16_f32 v37, v40, v41
	v_addc_co_u32_e32 v39, vcc, 0, v115, vcc
	global_store_dwordx4 v[38:39], v[34:37], off nt
	v_mul_f32_e32 v32, v28, v32
	v_mul_f32_e32 v33, v29, v33
	v_exp_f32_e32 v28, v28
	v_exp_f32_e32 v34, v26
	v_exp_f32_e32 v35, v27
	v_mul_f32_e32 v26, v26, v30
	v_mul_f32_e32 v27, v27, v31
	v_exp_f32_e32 v30, v18
	v_exp_f32_e32 v31, v19
	v_mul_f32_e32 v18, v18, v22
	v_mul_f32_e32 v19, v19, v23
	v_exp_f32_e32 v29, v29
	v_add_f32_e32 v30, 1.0, v30
	v_add_f32_e32 v31, 1.0, v31
	v_rcp_f32_e32 v30, v30
	v_rcp_f32_e32 v31, v31
	v_add_f32_e32 v34, 1.0, v34
	v_add_f32_e32 v35, 1.0, v35
	v_add_f32_e32 v28, 1.0, v28
	v_mul_f32_e32 v22, v30, v18
	v_mul_f32_e32 v23, v31, v19
	v_exp_f32_e32 v18, v20
	v_exp_f32_e32 v19, v21
	v_add_f32_e32 v29, 1.0, v29
	v_rcp_f32_e32 v34, v34
	v_add_f32_e32 v18, 1.0, v18
	v_add_f32_e32 v19, 1.0, v19
	v_rcp_f32_e32 v35, v35
	v_rcp_f32_e32 v28, v28
	v_rcp_f32_e32 v29, v29
	v_rcp_f32_e32 v18, v18
	v_rcp_f32_e32 v19, v19
	v_mul_f32_e32 v24, v20, v24
	v_mul_f32_e32 v25, v21, v25
	s_mov_b32 s9, 0x140000
	v_mul_f32_e32 v26, v34, v26
	v_mul_f32_e32 v27, v35, v27
	v_mul_f32_e32 v28, v28, v32
	v_mul_f32_e32 v29, v29, v33
	v_mul_f32_e32 v24, v18, v24
	v_mul_f32_e32 v25, v19, v25
	v_cvt_pk_bf16_f32 v20, v22, v23
	v_add_co_u32_e32 v22, vcc, s9, v114
	v_cvt_pk_bf16_f32 v18, v26, v27
	v_cvt_pk_bf16_f32 v19, v28, v29
	v_cvt_pk_bf16_f32 v21, v24, v25
	v_addc_co_u32_e32 v23, vcc, 0, v115, vcc
	global_store_dwordx4 v[22:23], v[18:21], off nt
	v_mul_f32_e32 v16, v12, v16
	v_mul_f32_e32 v17, v13, v17
	v_exp_f32_e32 v12, v12
	v_exp_f32_e32 v18, v10
	v_exp_f32_e32 v19, v11
	v_mul_f32_e32 v10, v10, v14
	v_mul_f32_e32 v11, v11, v15
	v_exp_f32_e32 v14, v2
	v_exp_f32_e32 v15, v3
	v_mul_f32_e32 v2, v2, v6
	v_mul_f32_e32 v3, v3, v7
	v_exp_f32_e32 v13, v13
	v_add_f32_e32 v14, 1.0, v14
	v_add_f32_e32 v15, 1.0, v15
	v_rcp_f32_e32 v14, v14
	v_rcp_f32_e32 v15, v15
	v_add_f32_e32 v18, 1.0, v18
	v_add_f32_e32 v19, 1.0, v19
	v_add_f32_e32 v12, 1.0, v12
	v_mul_f32_e32 v6, v14, v2
	v_mul_f32_e32 v7, v15, v3
	v_exp_f32_e32 v2, v4
	v_exp_f32_e32 v3, v5
	v_add_f32_e32 v13, 1.0, v13
	v_rcp_f32_e32 v18, v18
	v_add_f32_e32 v2, 1.0, v2
	v_add_f32_e32 v3, 1.0, v3
	v_rcp_f32_e32 v19, v19
	v_rcp_f32_e32 v12, v12
	v_rcp_f32_e32 v13, v13
	v_rcp_f32_e32 v2, v2
	v_rcp_f32_e32 v3, v3
	v_mul_f32_e32 v8, v4, v8
	v_mul_f32_e32 v9, v5, v9
	v_cvt_pk_bf16_f32 v4, v6, v7
	v_add_co_u32_e32 v6, vcc, 0x160000, v114
	v_mul_f32_e32 v10, v18, v10
	v_mul_f32_e32 v11, v19, v11
	v_mul_f32_e32 v12, v12, v16
	v_mul_f32_e32 v13, v13, v17
	v_mul_f32_e32 v8, v2, v8
	v_mul_f32_e32 v9, v3, v9
	v_addc_co_u32_e32 v7, vcc, 0, v115, vcc
	v_cvt_pk_bf16_f32 v2, v10, v11
	v_cvt_pk_bf16_f32 v3, v12, v13
	v_cvt_pk_bf16_f32 v5, v8, v9
	s_mov_b64 s[16:17], -1
	s_andn2_b64 vcc, exec, s[4:5]
	global_store_dwordx4 v[6:7], v[2:5], off nt
	s_cbranch_vccnz .LBB0_360
	s_andn2_b64 vcc, exec, s[0:1]
	s_cbranch_vccnz .LBB0_359
	s_barrier
	s_branch .LBB0_359
